# HGRN2 scan loop rewritten in shifted-state form E_t = S_t - v_t+1 (one packed fma per key pair, q-sum pass per chunk)
# speedup vs baseline: 1.0013x; 1.0013x over previous
; __device__ __forceinline__ void hg_task(const Params& p, int l, int task, char* smem) {
;     ...
;   u32x4 rq[2], rf[2], rv[2];
;   f32x2 S2[8];
; #pragma unroll
;   for (int i = 0; i < 8; ++i) S2[i] = mk2(0.f, 0.f);
;     ...
;   HG_PREFETCH(0);
.LBB0_149:
	s_lshr_b32 s48, s42, 3
	s_lshl_b32 s50, s48, 8
	s_and_b32 s45, s60, 1
	s_add_i32 s50, s50, 0x8000
	v_ashrrev_i32_e32 v168, 3, v27
	s_cmp_eq_u32 s45, 0
	v_sub_u32_e32 v0, 0xff, v168
	s_cselect_b64 s[40:41], -1, 0
	v_cndmask_b32_e64 v0, v0, v168, s[40:41]
	v_add_u32_e32 v0, s50, v0
	s_mul_i32 s98, s45, 0x1200000
	s_waitcnt vmcnt(0)
	v_mad_i64_i32 v[2:3], s[42:43], v0, s74, v[94:95]
	v_lshl_add_u64 v[28:29], v[90:91], 0, s[98:99]
	s_lshl_b32 s98, s44, 1
	s_lshl_b32 s42, s45, 9
	s_mov_b32 s43, s99
	v_add_u32_e32 v169, 32, v168
	v_sub_u32_e32 v12, 0xdf, v168
	v_lshl_add_u64 v[4:5], v[2:3], 0, s[98:99]
	v_lshl_add_u64 v[2:3], v[2:3], 0, s[42:43]
	v_cndmask_b32_e64 v12, v12, v169, s[40:41]
	v_lshlrev_b32_e32 v0, 1, v26
	v_lshl_add_u64 v[2:3], v[2:3], 0, s[98:99]
	v_add_u32_e32 v12, s50, v12
	v_lshl_add_u64 v[10:11], v[4:5], 0, v[0:1]
	v_lshl_add_u64 v[6:7], v[2:3], 0, v[0:1]
	s_waitcnt vmcnt(0)
	v_mad_i64_i32 v[18:19], s[46:47], v12, s74, v[94:95]
	global_load_dwordx4 v[2:5], v[10:11], off offset:2592
	s_nop 0
	global_load_dwordx4 v[6:9], v[6:7], off offset:3104
	v_add_co_u32_e32 v10, vcc, s76, v10
	v_lshl_add_u64 v[12:13], v[18:19], 0, s[98:99]
	s_nop 0
	v_addc_co_u32_e32 v11, vcc, 0, v11, vcc
	v_lshl_add_u64 v[20:21], v[12:13], 0, v[0:1]
	v_lshl_add_u64 v[18:19], v[18:19], 0, s[42:43]
	v_lshl_add_u64 v[18:19], v[18:19], 0, s[98:99]
	v_add_co_u32_e32 v22, vcc, s76, v20
	v_lshl_add_u64 v[18:19], v[18:19], 0, v[0:1]
	s_nop 0
	v_addc_co_u32_e32 v23, vcc, 0, v21, vcc
	global_load_dwordx4 v[10:13], v[10:11], off offset:32
	s_nop 0
	global_load_dwordx4 v[14:17], v[20:21], off offset:2592
	s_nop 0
	global_load_dwordx4 v[18:21], v[18:19], off offset:3104
	s_nop 0
	global_load_dwordx4 v[22:25], v[22:23], off offset:32
	v_ashrrev_i32_e32 v170, 2, v27
	v_bfe_u32 v31, v27, 2, 4
	s_mov_b32 s42, 0x3ffffff0
	v_and_or_b32 v0, v170, s42, v31
	v_lshlrev_b32_e32 v196, 2, v0
	v_lshlrev_b32_e32 v0, 4, v27
	v_and_b32_e32 v32, 3, v27
	v_and_b32_e32 v0, 48, v0
	v_lshlrev_b32_e32 v171, 6, v32
	v_cmp_eq_u32_e64 s[42:43], 0, v32
	v_lshlrev_b32_e32 v32, 2, v0
	v_lshl_add_u64 v[28:29], v[28:29], 0, s[98:99]
	v_lshlrev_b32_e32 v0, 1, v0
	v_lshl_add_u64 v[28:29], v[28:29], 0, v[0:1]
	s_mov_b64 s[30:31], 0x188a0000
	v_lshlrev_b32_e32 v30, 2, v26
	v_lshl_add_u64 v[138:139], v[28:29], 0, s[30:31]
	s_movk_i32 s30, 0x110
	v_mad_u64_u32 v[140:141], s[46:47], v168, s30, v[30:31]
	v_lshlrev_b32_e32 v29, 2, v31
	s_movk_i32 s30, 0xffc0
	s_lshl_b32 s45, s45, 8
	v_lshlrev_b32_e32 v0, 8, v168
	v_lshlrev_b32_e32 v28, 8, v169
	v_and_or_b32 v27, v27, s30, v29
	v_mov_b32_e32 v142, 0
	v_mov_b32_e32 v211, 0
	s_mov_b32 s52, 0
	s_lshl_b32 s51, s48, 11
	v_lshl_or_b32 v197, v170, 8, v32
	v_sub_f32_e32 v198, 1.0, v159
	v_sub_f32_e32 v199, 1.0, v135
	v_sub_f32_e32 v200, 1.0, v163
	v_sub_f32_e32 v201, 1.0, v162
	v_sub_f32_e32 v202, 1.0, v165
	v_sub_f32_e32 v203, 1.0, v164
	v_sub_f32_e32 v204, 1.0, v167
	v_sub_f32_e32 v205, 1.0, v166
	v_add_u32_e32 v141, 0x8800, v27
	v_or_b32_e32 v206, 0x110, v171
	v_add_u32_e32 v207, v30, v0
	v_add_u32_e32 v208, v30, v28
	s_lshl_b32 s98, s44, 1
	v_lshlrev_b32_e32 v0, 1, v26
	s_lshl_b32 s44, s45, 1
	v_mov_b32_e32 v143, v142
	v_mov_b32_e32 v156, v142
	v_mov_b32_e32 v157, v142
	v_mov_b32_e32 v154, v142
	v_mov_b32_e32 v155, v142
	v_mov_b32_e32 v152, v142
	v_mov_b32_e32 v153, v142
	v_mov_b32_e32 v150, v142
	v_mov_b32_e32 v151, v142
	v_mov_b32_e32 v148, v142
	v_mov_b32_e32 v149, v142
	v_mov_b32_e32 v146, v142
	v_mov_b32_e32 v147, v142
	v_mov_b32_e32 v144, v142
	v_mov_b32_e32 v145, v142
	s_branch .LBB0_151

; __device__ __forceinline__ void hg_task(const Params& p, int l, int task, char* smem) {
;     ...
;     {
;       float4 fA[4], qA[4], fB[4], qB[4];
;       float vA, vB;
;       HG_LD(0, fA, qA, vA);
; #pragma unroll 1
;       for (int t = 0; t < 64; t += 2) {
;         HG_LD(t + 1, fB, qB, vB);
;         HG_STEP(t, fA, qA, vA);
;         const int t2 = (t + 2 < 64) ? t + 2 : 63;
;         HG_LD(t2, fA, qA, vA);
;         HG_STEP(t + 1, fB, qB, vB);
;       }
;     }
.LBB0_153:
	s_movk_i32 s45, 0x110
	v_mad_u32_u24 v234, v170, s45, v171
	ds_read_b128 v[26:29], v234
	ds_read_b128 v[30:33], v234 offset:16
	ds_read_b128 v[34:37], v234 offset:32
	ds_read_b128 v[38:41], v234 offset:48
	ds_read_b32 v42, v196 offset:50944
	v_lshlrev_b32_e32 v235, 2, v170
	v_mov_b32_e32 v209, v171
	v_mov_b32_e32 v210, v196
	v_mov_b32_e32 v236, 0
	s_waitcnt lgkmcnt(0)
	v_pk_add_f32 v[26:27], v[26:27], v[28:29]
	v_pk_add_f32 v[30:31], v[30:31], v[32:33]
	v_pk_add_f32 v[34:35], v[34:35], v[36:37]
	v_pk_add_f32 v[38:39], v[38:39], v[40:41]
	v_pk_add_f32 v[26:27], v[26:27], v[30:31]
	v_pk_add_f32 v[34:35], v[34:35], v[38:39]
	v_pk_add_f32 v[26:27], v[26:27], v[34:35]
	ds_write2st64_b32 v196, v42, v42 offset0:200 offset1:201
	v_add_f32_e32 v26, v26, v27
	s_nop 1
	v_add_f32_dpp v26, v26, v26 quad_perm:[1,0,3,2] row_mask:0xf bank_mask:0xf
	s_nop 1
	v_add_f32_dpp v26, v26, v26 quad_perm:[2,3,0,1] row_mask:0xf bank_mask:0xf
	s_nop 0
	ds_write_b32 v235, v26 offset:53248
	s_waitcnt lgkmcnt(0)
	s_barrier
	ds_read_b128 v[26:29], v209 offset:0
	ds_read_b128 v[30:33], v209 offset:16
	ds_read_b128 v[34:37], v209 offset:32
	ds_read_b128 v[38:41], v209 offset:48
	ds_read_b128 v[42:45], v209 offset:17408
	ds_read_b128 v[46:49], v209 offset:17424
	ds_read_b128 v[50:53], v209 offset:17440
	ds_read_b128 v[54:57], v209 offset:17456
	ds_read_b32 v216, v236 offset:53248
	ds_read2st64_b32 v[212:213], v210 offset0:136 offset1:137
	s_waitcnt lgkmcnt(0)
	v_sub_f32_e32 v224, v211, v212
	v_pk_add_f32 v[142:143], v[142:143], v[224:225] op_sel_hi:[1,0]
	v_pk_add_f32 v[156:157], v[156:157], v[224:225] op_sel_hi:[1,0]
	v_pk_add_f32 v[154:155], v[154:155], v[224:225] op_sel_hi:[1,0]
	v_pk_add_f32 v[152:153], v[152:153], v[224:225] op_sel_hi:[1,0]
	v_pk_add_f32 v[150:151], v[150:151], v[224:225] op_sel_hi:[1,0]
	v_pk_add_f32 v[148:149], v[148:149], v[224:225] op_sel_hi:[1,0]
	v_pk_add_f32 v[146:147], v[146:147], v[224:225] op_sel_hi:[1,0]
	v_pk_add_f32 v[144:145], v[144:145], v[224:225] op_sel_hi:[1,0]
	s_mov_b32 s45, 0
.Lhg_it:
	s_waitcnt lgkmcnt(0)
	ds_read_b128 v[58:61], v209 offset:272
	ds_read_b128 v[62:65], v209 offset:288
	ds_read_b128 v[66:69], v209 offset:304
	ds_read_b128 v[70:73], v209 offset:320
	ds_read_b128 v[74:77], v209 offset:17680
	ds_read_b128 v[78:81], v209 offset:17696
	ds_read_b128 v[82:85], v209 offset:17712
	ds_read_b128 v[86:89], v209 offset:17728
	ds_read_b32 v217, v236 offset:53252
	ds_read2st64_b32 v[214:215], v210 offset0:138 offset1:139
	v_sub_f32_e32 v224, v212, v213
	v_mul_f32_e32 v232, v213, v216
	v_pk_fma_f32 v[142:143], v[42:43], v[142:143], v[224:225] op_sel_hi:[1,1,0]
	v_pk_fma_f32 v[156:157], v[44:45], v[156:157], v[224:225] op_sel_hi:[1,1,0]
	v_pk_fma_f32 v[154:155], v[46:47], v[154:155], v[224:225] op_sel_hi:[1,1,0]
	v_pk_fma_f32 v[152:153], v[48:49], v[152:153], v[224:225] op_sel_hi:[1,1,0]
	v_pk_fma_f32 v[150:151], v[50:51], v[150:151], v[224:225] op_sel_hi:[1,1,0]
	v_pk_fma_f32 v[148:149], v[52:53], v[148:149], v[224:225] op_sel_hi:[1,1,0]
	v_pk_fma_f32 v[146:147], v[54:55], v[146:147], v[224:225] op_sel_hi:[1,1,0]
	v_pk_fma_f32 v[144:145], v[56:57], v[144:145], v[224:225] op_sel_hi:[1,1,0]
	v_pk_mul_f32 v[226:227], v[26:27], v[142:143]
	v_pk_mul_f32 v[228:229], v[28:29], v[156:157]
	v_pk_fma_f32 v[226:227], v[30:31], v[154:155], v[226:227]
	v_pk_fma_f32 v[228:229], v[32:33], v[152:153], v[228:229]
	v_pk_fma_f32 v[226:227], v[34:35], v[150:151], v[226:227]
	v_pk_fma_f32 v[228:229], v[36:37], v[148:149], v[228:229]
	v_pk_fma_f32 v[226:227], v[38:39], v[146:147], v[226:227]
	v_pk_fma_f32 v[228:229], v[40:41], v[144:145], v[228:229]
	v_add_f32_e32 v226, v226, v227
	v_add_f32_e32 v228, v228, v229
	v_add_f32_e32 v230, v226, v228
	s_waitcnt lgkmcnt(0)
	ds_read_b128 v[26:29], v209 offset:544
	ds_read_b128 v[30:33], v209 offset:560
	ds_read_b128 v[34:37], v209 offset:576
	ds_read_b128 v[38:41], v209 offset:592
	ds_read_b128 v[42:45], v209 offset:17952
	ds_read_b128 v[46:49], v209 offset:17968
	ds_read_b128 v[50:53], v209 offset:17984
	ds_read_b128 v[54:57], v209 offset:18000
	ds_read_b32 v216, v236 offset:53256
	v_sub_f32_e32 v224, v213, v214
	v_mul_f32_e32 v233, v214, v217
	v_pk_fma_f32 v[142:143], v[74:75], v[142:143], v[224:225] op_sel_hi:[1,1,0]
	v_pk_fma_f32 v[156:157], v[76:77], v[156:157], v[224:225] op_sel_hi:[1,1,0]
	v_add_f32_dpp v230, v230, v230 quad_perm:[1,0,3,2] row_mask:0xf bank_mask:0xf
	v_pk_fma_f32 v[154:155], v[78:79], v[154:155], v[224:225] op_sel_hi:[1,1,0]
	v_pk_fma_f32 v[152:153], v[80:81], v[152:153], v[224:225] op_sel_hi:[1,1,0]
	v_add_f32_dpp v230, v230, v230 quad_perm:[2,3,0,1] row_mask:0xf bank_mask:0xf
	v_pk_fma_f32 v[150:151], v[82:83], v[150:151], v[224:225] op_sel_hi:[1,1,0]
	v_pk_fma_f32 v[148:149], v[84:85], v[148:149], v[224:225] op_sel_hi:[1,1,0]
	v_add_f32_e32 v230, v230, v232
	ds_write_b32 v210, v230 offset:34816
	v_pk_fma_f32 v[146:147], v[86:87], v[146:147], v[224:225] op_sel_hi:[1,1,0]
	v_pk_fma_f32 v[144:145], v[88:89], v[144:145], v[224:225] op_sel_hi:[1,1,0]
	v_pk_mul_f32 v[226:227], v[58:59], v[142:143]
	v_pk_mul_f32 v[228:229], v[60:61], v[156:157]
	v_pk_fma_f32 v[226:227], v[62:63], v[154:155], v[226:227]
	v_pk_fma_f32 v[228:229], v[64:65], v[152:153], v[228:229]
	v_pk_fma_f32 v[226:227], v[66:67], v[150:151], v[226:227]
	v_pk_fma_f32 v[228:229], v[68:69], v[148:149], v[228:229]
	v_pk_fma_f32 v[226:227], v[70:71], v[146:147], v[226:227]
	v_pk_fma_f32 v[228:229], v[72:73], v[144:145], v[228:229]
	v_add_f32_e32 v226, v226, v227
	v_add_f32_e32 v228, v228, v229
	v_add_f32_e32 v231, v226, v228
	s_waitcnt lgkmcnt(0)
; __device__ __forceinline__ void hg_task(const Params& p, int l, int task, char* smem) {
;     ...
;     {
;       float4 fA[4], qA[4], fB[4], qB[4];
;       float vA, vB;
;       HG_LD(0, fA, qA, vA);
; #pragma unroll 1
;       for (int t = 0; t < 64; t += 2) {
;         HG_LD(t + 1, fB, qB, vB);
;         HG_STEP(t, fA, qA, vA);
;         const int t2 = (t + 2 < 64) ? t + 2 : 63;
;         HG_LD(t2, fA, qA, vA);
;         HG_STEP(t + 1, fB, qB, vB);
;       }
;     }
	ds_read_b128 v[58:61], v209 offset:816
	ds_read_b128 v[62:65], v209 offset:832
	ds_read_b128 v[66:69], v209 offset:848
	ds_read_b128 v[70:73], v209 offset:864
	ds_read_b128 v[74:77], v209 offset:18224
	ds_read_b128 v[78:81], v209 offset:18240
	ds_read_b128 v[82:85], v209 offset:18256
	ds_read_b128 v[86:89], v209 offset:18272
	ds_read_b32 v217, v236 offset:53260
	ds_read2st64_b32 v[212:213], v210 offset0:140 offset1:141
	v_sub_f32_e32 v224, v214, v215
	v_mul_f32_e32 v232, v215, v216
	v_pk_fma_f32 v[142:143], v[42:43], v[142:143], v[224:225] op_sel_hi:[1,1,0]
	v_pk_fma_f32 v[156:157], v[44:45], v[156:157], v[224:225] op_sel_hi:[1,1,0]
	v_add_f32_dpp v231, v231, v231 quad_perm:[1,0,3,2] row_mask:0xf bank_mask:0xf
	v_pk_fma_f32 v[154:155], v[46:47], v[154:155], v[224:225] op_sel_hi:[1,1,0]
	v_pk_fma_f32 v[152:153], v[48:49], v[152:153], v[224:225] op_sel_hi:[1,1,0]
	v_add_f32_dpp v231, v231, v231 quad_perm:[2,3,0,1] row_mask:0xf bank_mask:0xf
	v_pk_fma_f32 v[150:151], v[50:51], v[150:151], v[224:225] op_sel_hi:[1,1,0]
	v_pk_fma_f32 v[148:149], v[52:53], v[148:149], v[224:225] op_sel_hi:[1,1,0]
	v_add_f32_e32 v231, v231, v233
	ds_write_b32 v210, v231 offset:35072
	v_pk_fma_f32 v[146:147], v[54:55], v[146:147], v[224:225] op_sel_hi:[1,1,0]
	v_pk_fma_f32 v[144:145], v[56:57], v[144:145], v[224:225] op_sel_hi:[1,1,0]
	v_pk_mul_f32 v[226:227], v[26:27], v[142:143]
	v_pk_mul_f32 v[228:229], v[28:29], v[156:157]
	v_pk_fma_f32 v[226:227], v[30:31], v[154:155], v[226:227]
	v_pk_fma_f32 v[228:229], v[32:33], v[152:153], v[228:229]
	v_pk_fma_f32 v[226:227], v[34:35], v[150:151], v[226:227]
	v_pk_fma_f32 v[228:229], v[36:37], v[148:149], v[228:229]
	v_pk_fma_f32 v[226:227], v[38:39], v[146:147], v[226:227]
	v_pk_fma_f32 v[228:229], v[40:41], v[144:145], v[228:229]
	v_add_f32_e32 v226, v226, v227
	v_add_f32_e32 v228, v228, v229
	v_add_f32_e32 v230, v226, v228
	s_waitcnt lgkmcnt(0)
	ds_read_b128 v[26:29], v209 offset:1088
	ds_read_b128 v[30:33], v209 offset:1104
	ds_read_b128 v[34:37], v209 offset:1120
	ds_read_b128 v[38:41], v209 offset:1136
	ds_read_b128 v[42:45], v209 offset:18496
	ds_read_b128 v[46:49], v209 offset:18512
	ds_read_b128 v[50:53], v209 offset:18528
	ds_read_b128 v[54:57], v209 offset:18544
	ds_read_b32 v216, v236 offset:53264
	v_sub_f32_e32 v224, v215, v212
	v_mul_f32_e32 v233, v212, v217
	v_pk_fma_f32 v[142:143], v[74:75], v[142:143], v[224:225] op_sel_hi:[1,1,0]
	v_pk_fma_f32 v[156:157], v[76:77], v[156:157], v[224:225] op_sel_hi:[1,1,0]
	v_add_f32_dpp v230, v230, v230 quad_perm:[1,0,3,2] row_mask:0xf bank_mask:0xf
	v_pk_fma_f32 v[154:155], v[78:79], v[154:155], v[224:225] op_sel_hi:[1,1,0]
	v_pk_fma_f32 v[152:153], v[80:81], v[152:153], v[224:225] op_sel_hi:[1,1,0]
	v_add_f32_dpp v230, v230, v230 quad_perm:[2,3,0,1] row_mask:0xf bank_mask:0xf
	v_pk_fma_f32 v[150:151], v[82:83], v[150:151], v[224:225] op_sel_hi:[1,1,0]
	v_pk_fma_f32 v[148:149], v[84:85], v[148:149], v[224:225] op_sel_hi:[1,1,0]
	v_add_f32_e32 v230, v230, v232
	ds_write_b32 v210, v230 offset:35328
	v_pk_fma_f32 v[146:147], v[86:87], v[146:147], v[224:225] op_sel_hi:[1,1,0]
	v_pk_fma_f32 v[144:145], v[88:89], v[144:145], v[224:225] op_sel_hi:[1,1,0]
	v_pk_mul_f32 v[226:227], v[58:59], v[142:143]
	v_pk_mul_f32 v[228:229], v[60:61], v[156:157]
	v_pk_fma_f32 v[226:227], v[62:63], v[154:155], v[226:227]
	v_pk_fma_f32 v[228:229], v[64:65], v[152:153], v[228:229]
	v_pk_fma_f32 v[226:227], v[66:67], v[150:151], v[226:227]
	v_pk_fma_f32 v[228:229], v[68:69], v[148:149], v[228:229]
	v_pk_fma_f32 v[226:227], v[70:71], v[146:147], v[226:227]
	v_pk_fma_f32 v[228:229], v[72:73], v[144:145], v[228:229]
	v_add_f32_e32 v226, v226, v227
	v_add_f32_e32 v228, v228, v229
	v_add_f32_e32 v231, v226, v228
	s_nop 1
	v_add_f32_dpp v231, v231, v231 quad_perm:[1,0,3,2] row_mask:0xf bank_mask:0xf
	s_nop 1
	v_add_f32_dpp v231, v231, v231 quad_perm:[2,3,0,1] row_mask:0xf bank_mask:0xf
	s_nop 0
	v_add_f32_e32 v231, v231, v233
	ds_write_b32 v210, v231 offset:35584
	v_add_u32_e32 v209, 0x440, v209
	v_add_u32_e32 v210, 0x400, v210
	v_add_u32_e32 v236, 16, v236
	s_add_i32 s45, s45, 1
	s_cmp_lt_u32 s45, 16
	s_cbranch_scc1 .Lhg_it
	v_mov_b32_e32 v211, v215
	s_branch .LBB0_150
